# k1tail
# baseline (speedup 1.0000x reference)
; #define PG8_STAGE(bufoff, gbase, voff) do { _Pragma("unroll") for (int _i = 0; _i < 2; ++_i) \
;         __builtin_amdgcn_global_load_lds((const unsigned*)((const char*)(gbase) + (voff)[_i]), (LAS unsigned*)(lds + (bufoff) + ldsw + _i * 8192), 16, 0, 0); } while (0)
; #define PG8_LDA(dst, b, h) do { _Pragma("unroll") for (int m = 0; m < 4; ++m) _Pragma("unroll") for (int k = 0; k < 2; ++k) dst[m][k] = *(const LAS bf16x8*)(lds + PG8_SA(b, h) + aoff + m * 2048 + k * 1024); } while (0)
; #define PG8_LDB(dst, b, h) do { _Pragma("unroll") for (int n = 0; n < 2; ++n) _Pragma("unroll") for (int k = 0; k < 2; ++k) dst[n][k] = *(const LAS bf16x8*)(lds + PG8_SB(b, h) + boff + n * 2048 + k * 1024); } while (0)
; #define PG8_MMA(ai, bj, At, Bt) do { __builtin_amdgcn_s_setprio(1); _Pragma("unroll") for (int m = 0; m < 4; ++m) _Pragma("unroll") for (int n = 0; n < 2; ++n) _Pragma("unroll") for (int k = 0; k < 2; ++k) \
;         acc[ai][bj][m][n] = __builtin_amdgcn_mfma_f32_16x16x32_bf16(Bt[n][k], At[m][k], acc[ai][bj][m][n], 0, 0, 0); __builtin_amdgcn_s_setprio(0); } while (0)
; #define PG8_WAIT_L(n) asm volatile("s_waitcnt lgkmcnt(" #n ")" ::: "memory")
; #define PG8_BAR __builtin_amdgcn_s_barrier()
; #define PG8_SCHED __builtin_amdgcn_sched_barrier(0)
; template <class Epi, class Job>
; __device__ __forceinline__ void gemm_phase(LAS unsigned char* lds, const Job& S, const Epi& E) {
;     ...
;         for (int t = 0; t < nt; t += 2) {
;             const bool last = (t == nt - 2);
;             const char* a1 = cA + (size_t)(t + 1) * kstep;
;             const char* a2 = last ? nA : cA + (size_t)(t + 2) * kstep; const char* b2 = last ? nB : cB + (size_t)(t + 2) * kstep;
;             const char* a3 = a2 + kstep; const char* b3 = b2 + kstep;
;             PG8_LDB(B0, 0, 0); PG8_SCHED; PG8_LDA(At, 0, 0); PG8_STAGE(PG8_SA(1, 1), a1 + hstepA, voffA);
;             PG8_WAIT_L(8); PG8_BAR; PG8_WAIT_L(0); PG8_MMA(0, 0, At, B0); PG8_BAR; PG8_SCHED;
;             PG8_LDB(B1, 0, 1); PG8_STAGE(PG8_SB(0, 0), b2, voffB);
;     ...
;         for (int a = 0; a < 2; ++a)
; #pragma unroll
;             for (int b = 0; b < 2; ++b)
; #pragma unroll
;                 for (int m = 0; m < 4; ++m)
; #pragma unroll
;                     for (int n = 0; n < 2; ++n) acc[a][b][m][n] = (f32x4){0.f, 0.f, 0.f, 0.f};
.LBB0_185:
	s_add_u32 s28, s28, 0x100080
	s_addc_u32 s29, s29, 0
	s_add_u32 s27, s36, 0x100
	v_mov_b32_e32 v0, 0
	s_addc_u32 s67, s37, 0
	s_mov_b32 s68, -2
	v_mov_b32_e32 v1, v0
	v_mov_b32_e32 v2, v0
	v_mov_b32_e32 v3, v0
	v_mov_b32_e32 v4, v0
	v_mov_b32_e32 v5, v0
	v_mov_b32_e32 v6, v0
	v_mov_b32_e32 v7, v0
	v_mov_b32_e32 v8, v0
	v_mov_b32_e32 v9, v0
	v_mov_b32_e32 v10, v0
	v_mov_b32_e32 v11, v0
	v_mov_b32_e32 v16, v0
	v_mov_b32_e32 v17, v0
	v_mov_b32_e32 v18, v0
	v_mov_b32_e32 v19, v0
	v_mov_b32_e32 v24, v0
	v_mov_b32_e32 v25, v0
	v_mov_b32_e32 v26, v0
	v_mov_b32_e32 v27, v0
	v_mov_b32_e32 v32, v0
	v_mov_b32_e32 v33, v0
	v_mov_b32_e32 v34, v0
	v_mov_b32_e32 v35, v0
	v_mov_b32_e32 v40, v0
	v_mov_b32_e32 v41, v0
	v_mov_b32_e32 v42, v0
	v_mov_b32_e32 v43, v0
	v_mov_b32_e32 v48, v0
	v_mov_b32_e32 v49, v0
	v_mov_b32_e32 v50, v0
	v_mov_b32_e32 v51, v0
	v_mov_b32_e32 v12, v0
	v_mov_b32_e32 v13, v0
	v_mov_b32_e32 v14, v0
	v_mov_b32_e32 v15, v0
	v_mov_b32_e32 v20, v0
	v_mov_b32_e32 v21, v0
	v_mov_b32_e32 v22, v0
	v_mov_b32_e32 v23, v0
	v_mov_b32_e32 v28, v0
	v_mov_b32_e32 v29, v0
	v_mov_b32_e32 v30, v0
	v_mov_b32_e32 v31, v0
	v_mov_b32_e32 v36, v0
	v_mov_b32_e32 v37, v0
	v_mov_b32_e32 v38, v0
	v_mov_b32_e32 v39, v0
	v_mov_b32_e32 v44, v0
	v_mov_b32_e32 v45, v0
	v_mov_b32_e32 v46, v0
	v_mov_b32_e32 v47, v0
	v_mov_b32_e32 v52, v0
	v_mov_b32_e32 v53, v0
	v_mov_b32_e32 v54, v0
	v_mov_b32_e32 v55, v0
	v_mov_b32_e32 v56, v0
	v_mov_b32_e32 v57, v0
	v_mov_b32_e32 v58, v0
	v_mov_b32_e32 v59, v0
	v_mov_b32_e32 v60, v0
	v_mov_b32_e32 v61, v0
	v_mov_b32_e32 v62, v0
	v_mov_b32_e32 v63, v0
	v_mov_b32_e32 v64, v0
	v_mov_b32_e32 v65, v0
	v_mov_b32_e32 v66, v0
	v_mov_b32_e32 v67, v0
	v_mov_b32_e32 v68, v0
	v_mov_b32_e32 v69, v0
	v_mov_b32_e32 v70, v0
	v_mov_b32_e32 v71, v0
	v_mov_b32_e32 v72, v0
	v_mov_b32_e32 v73, v0
	v_mov_b32_e32 v74, v0
	v_mov_b32_e32 v75, v0
	v_mov_b32_e32 v80, v0
	v_mov_b32_e32 v81, v0
	v_mov_b32_e32 v82, v0
	v_mov_b32_e32 v83, v0
	v_mov_b32_e32 v88, v0
	v_mov_b32_e32 v89, v0
	v_mov_b32_e32 v90, v0
	v_mov_b32_e32 v91, v0
	v_mov_b32_e32 v96, v0
	v_mov_b32_e32 v97, v0
	v_mov_b32_e32 v98, v0
	v_mov_b32_e32 v99, v0
	v_mov_b32_e32 v108, v0
	v_mov_b32_e32 v109, v0
	v_mov_b32_e32 v110, v0
	v_mov_b32_e32 v111, v0
	v_mov_b32_e32 v116, v0
	v_mov_b32_e32 v117, v0
	v_mov_b32_e32 v118, v0
	v_mov_b32_e32 v119, v0
	v_mov_b32_e32 v76, v0
	v_mov_b32_e32 v77, v0
	v_mov_b32_e32 v78, v0
	v_mov_b32_e32 v79, v0
	v_mov_b32_e32 v84, v0
	v_mov_b32_e32 v85, v0
	v_mov_b32_e32 v86, v0
	v_mov_b32_e32 v87, v0
	v_mov_b32_e32 v92, v0
	v_mov_b32_e32 v93, v0
	v_mov_b32_e32 v94, v0
	v_mov_b32_e32 v95, v0
	v_mov_b32_e32 v100, v0
	v_mov_b32_e32 v101, v0
	v_mov_b32_e32 v102, v0
	v_mov_b32_e32 v103, v0
	v_mov_b32_e32 v104, v0
	v_mov_b32_e32 v105, v0
	v_mov_b32_e32 v106, v0
	v_mov_b32_e32 v107, v0
	v_mov_b32_e32 v112, v0
	v_mov_b32_e32 v113, v0
	v_mov_b32_e32 v114, v0
	v_mov_b32_e32 v115, v0
	v_mov_b32_e32 v120, v0
	v_mov_b32_e32 v121, v0
	v_mov_b32_e32 v122, v0
	v_mov_b32_e32 v123, v0
	v_mov_b32_e32 v124, v0
	v_mov_b32_e32 v125, v0
	v_mov_b32_e32 v126, v0
	v_mov_b32_e32 v127, v0
	ds_read_b128 v[158:161], v154
	ds_read_b128 v[174:177], v154 offset:1024
	ds_read_b128 v[178:181], v154 offset:2048
	ds_read_b128 v[182:185], v154 offset:3072
	ds_read_b128 v[186:189], v155
	ds_read_b128 v[194:197], v155 offset:2048
	ds_read_b128 v[202:205], v155 offset:4096
	ds_read_b128 v[210:213], v155 offset:6144
	ds_read_b128 v[190:193], v155 offset:1024
	ds_read_b128 v[198:201], v155 offset:3072
	ds_read_b128 v[206:209], v155 offset:5120
	ds_read_b128 v[214:217], v155 offset:7168
.LBB0_186:
	s_add_i32 m0, s52, 0xc000
	s_nop 0
	global_load_lds_dwordx4 v144, s[28:29]
	s_add_i32 m0, s52, 0xe000
	s_nop 0
	global_load_lds_dwordx4 v146, s[28:29]
	s_add_u32 s36, s28, 0xfff00080
	s_addc_u32 s37, s29, -1
	s_cmp_eq_u32 s68, 60
	s_cselect_b32 s47, s23, s37
	s_cselect_b32 s46, s22, s36
	s_cselect_b32 s37, s25, s67
	s_cselect_b32 s36, s24, s27
	s_waitcnt lgkmcnt(8)
	s_waitcnt lgkmcnt(0)
	s_setprio 1
	s_barrier
	v_mfma_f32_16x16x32_bf16 v[124:127], v[158:161], v[186:189], v[124:127]
	ds_read_b128 v[218:221], v156
	v_mfma_f32_16x16x32_bf16 v[120:123], v[178:181], v[186:189], v[120:123]
	v_mfma_f32_16x16x32_bf16 v[112:115], v[158:161], v[194:197], v[112:115]
	ds_read_b128 v[222:225], v156 offset:1024
	v_mfma_f32_16x16x32_bf16 v[104:107], v[178:181], v[194:197], v[104:107]
	v_mfma_f32_16x16x32_bf16 v[100:103], v[158:161], v[202:205], v[100:103]
	ds_read_b128 v[226:229], v156 offset:2048
	v_mfma_f32_16x16x32_bf16 v[92:95], v[178:181], v[202:205], v[92:95]
	v_mfma_f32_16x16x32_bf16 v[84:87], v[158:161], v[210:213], v[84:87]
	ds_read_b128 v[230:233], v156 offset:3072
	v_mfma_f32_16x16x32_bf16 v[76:79], v[178:181], v[210:213], v[76:79]
	v_mfma_f32_16x16x32_bf16 v[124:127], v[174:177], v[190:193], v[124:127]
	v_mfma_f32_16x16x32_bf16 v[120:123], v[182:185], v[190:193], v[120:123]
	v_mfma_f32_16x16x32_bf16 v[112:115], v[174:177], v[198:201], v[112:115]
	v_mfma_f32_16x16x32_bf16 v[104:107], v[182:185], v[198:201], v[104:107]
	v_mfma_f32_16x16x32_bf16 v[100:103], v[174:177], v[206:209], v[100:103]
	v_mfma_f32_16x16x32_bf16 v[92:95], v[182:185], v[206:209], v[92:95]
	v_mfma_f32_16x16x32_bf16 v[84:87], v[174:177], v[214:217], v[84:87]
	v_mfma_f32_16x16x32_bf16 v[76:79], v[182:185], v[214:217], v[76:79]
	s_barrier
	s_setprio 0
	s_add_i32 s69, s60, s49
	s_mov_b32 m0, s69
	s_nop 0
	global_load_lds_dwordx4 v136, s[36:37]
	s_add_i32 m0, s69, 0x2000
	s_nop 0
	global_load_lds_dwordx4 v140, s[36:37]
	s_waitcnt lgkmcnt(0)
	s_setprio 1
	s_barrier
; #define PG8_STAGE(bufoff, gbase, voff) do { _Pragma("unroll") for (int _i = 0; _i < 2; ++_i) \
;         __builtin_amdgcn_global_load_lds((const unsigned*)((const char*)(gbase) + (voff)[_i]), (LAS unsigned*)(lds + (bufoff) + ldsw + _i * 8192), 16, 0, 0); } while (0)
; #define PG8_LDA(dst, b, h) do { _Pragma("unroll") for (int m = 0; m < 4; ++m) _Pragma("unroll") for (int k = 0; k < 2; ++k) dst[m][k] = *(const LAS bf16x8*)(lds + PG8_SA(b, h) + aoff + m * 2048 + k * 1024); } while (0)
; #define PG8_LDB(dst, b, h) do { _Pragma("unroll") for (int n = 0; n < 2; ++n) _Pragma("unroll") for (int k = 0; k < 2; ++k) dst[n][k] = *(const LAS bf16x8*)(lds + PG8_SB(b, h) + boff + n * 2048 + k * 1024); } while (0)
; #define PG8_MMA(ai, bj, At, Bt) do { __builtin_amdgcn_s_setprio(1); _Pragma("unroll") for (int m = 0; m < 4; ++m) _Pragma("unroll") for (int n = 0; n < 2; ++n) _Pragma("unroll") for (int k = 0; k < 2; ++k) \
;         acc[ai][bj][m][n] = __builtin_amdgcn_mfma_f32_16x16x32_bf16(Bt[n][k], At[m][k], acc[ai][bj][m][n], 0, 0, 0); __builtin_amdgcn_s_setprio(0); } while (0)
; #define PG8_WAIT_V(n) asm volatile("s_waitcnt vmcnt(" #n ")" ::: "memory")
; #define PG8_WAIT_L(n) asm volatile("s_waitcnt lgkmcnt(" #n ")" ::: "memory")
; #define PG8_BAR __builtin_amdgcn_s_barrier()
; #define PG8_SCHED __builtin_amdgcn_sched_barrier(0)
; template <class Epi, class Job>
; __device__ __forceinline__ void gemm_phase(LAS unsigned char* lds, const Job& S, const Epi& E) {
;     ...
;             PG8_BAR; PG8_WAIT_L(0); PG8_MMA(0, 1, At, B1); PG8_BAR;
;             PG8_LDA(At, 0, 1); PG8_STAGE(PG8_SA(0, 0), a2, voffA);
;             PG8_BAR; PG8_WAIT_L(0); PG8_MMA(1, 0, At, B0); PG8_BAR; PG8_SCHED;
;             PG8_STAGE(PG8_SB(0, 1), b2 + hstepB, voffB);
;             PG8_WAIT_V(6); PG8_BAR; PG8_MMA(1, 1, At, B1); PG8_BAR;
;             PG8_LDB(B0, 1, 0); PG8_SCHED; PG8_LDA(At, 1, 0); PG8_STAGE(PG8_SA(0, 1), a2 + hstepA, voffA);
;             PG8_WAIT_L(8); PG8_BAR; PG8_WAIT_L(0); PG8_MMA(0, 0, At, B0); PG8_BAR; PG8_SCHED;
	v_mfma_f32_16x16x32_bf16 v[116:119], v[218:221], v[186:189], v[116:119]
	v_mfma_f32_16x16x32_bf16 v[108:111], v[226:229], v[186:189], v[108:111]
	v_mfma_f32_16x16x32_bf16 v[96:99], v[218:221], v[194:197], v[96:99]
	v_mfma_f32_16x16x32_bf16 v[88:91], v[226:229], v[194:197], v[88:91]
	v_mfma_f32_16x16x32_bf16 v[80:83], v[218:221], v[202:205], v[80:83]
	v_mfma_f32_16x16x32_bf16 v[72:75], v[226:229], v[202:205], v[72:75]
	v_mfma_f32_16x16x32_bf16 v[68:71], v[218:221], v[210:213], v[68:71]
	v_mfma_f32_16x16x32_bf16 v[64:67], v[226:229], v[210:213], v[64:67]
	v_mfma_f32_16x16x32_bf16 v[116:119], v[222:225], v[190:193], v[116:119]
	ds_read_b128 v[186:189], v155 offset:16384
	v_mfma_f32_16x16x32_bf16 v[108:111], v[230:233], v[190:193], v[108:111]
	v_mfma_f32_16x16x32_bf16 v[96:99], v[222:225], v[198:201], v[96:99]
	ds_read_b128 v[194:197], v155 offset:18432
	v_mfma_f32_16x16x32_bf16 v[88:91], v[230:233], v[198:201], v[88:91]
	v_mfma_f32_16x16x32_bf16 v[80:83], v[222:225], v[206:209], v[80:83]
	ds_read_b128 v[202:205], v155 offset:20480
	v_mfma_f32_16x16x32_bf16 v[72:75], v[230:233], v[206:209], v[72:75]
	v_mfma_f32_16x16x32_bf16 v[68:71], v[222:225], v[214:217], v[68:71]
	ds_read_b128 v[210:213], v155 offset:22528
	v_mfma_f32_16x16x32_bf16 v[64:67], v[230:233], v[214:217], v[64:67]
	ds_read_b128 v[190:193], v155 offset:17408
	ds_read_b128 v[198:201], v155 offset:19456
	ds_read_b128 v[206:209], v155 offset:21504
	ds_read_b128 v[214:217], v155 offset:23552
	s_barrier
	s_setprio 0
	s_mov_b32 m0, s52
	s_mov_b64 s[100:101], s[46:47]
	global_load_lds_dwordx4 v134, s[46:47]
	s_mov_b32 m0, s53
	s_nop 0
	global_load_lds_dwordx4 v138, s[46:47]
	s_waitcnt vmcnt(8)
	s_waitcnt lgkmcnt(0)
	s_setprio 1
	s_barrier
	v_mfma_f32_16x16x32_bf16 v[60:63], v[158:161], v[186:189], v[60:63]
	v_mfma_f32_16x16x32_bf16 v[56:59], v[178:181], v[186:189], v[56:59]
	v_mfma_f32_16x16x32_bf16 v[52:55], v[158:161], v[194:197], v[52:55]
	v_mfma_f32_16x16x32_bf16 v[44:47], v[178:181], v[194:197], v[44:47]
	v_mfma_f32_16x16x32_bf16 v[36:39], v[158:161], v[202:205], v[36:39]
	v_mfma_f32_16x16x32_bf16 v[28:31], v[178:181], v[202:205], v[28:31]
	v_mfma_f32_16x16x32_bf16 v[20:23], v[158:161], v[210:213], v[20:23]
	v_mfma_f32_16x16x32_bf16 v[12:15], v[178:181], v[210:213], v[12:15]
	v_mfma_f32_16x16x32_bf16 v[60:63], v[174:177], v[190:193], v[60:63]
	v_mfma_f32_16x16x32_bf16 v[56:59], v[182:185], v[190:193], v[56:59]
	v_mfma_f32_16x16x32_bf16 v[52:55], v[174:177], v[198:201], v[52:55]
	v_mfma_f32_16x16x32_bf16 v[44:47], v[182:185], v[198:201], v[44:47]
	v_mfma_f32_16x16x32_bf16 v[36:39], v[174:177], v[206:209], v[36:39]
	v_mfma_f32_16x16x32_bf16 v[28:31], v[182:185], v[206:209], v[28:31]
	v_mfma_f32_16x16x32_bf16 v[20:23], v[174:177], v[214:217], v[20:23]
	v_mfma_f32_16x16x32_bf16 v[12:15], v[182:185], v[214:217], v[12:15]
	s_barrier
	s_setprio 0
	s_add_u32 s70, s36, 0x100000
	s_addc_u32 s71, s37, 0
	s_add_i32 s69, s61, s49
	s_mov_b32 m0, s69
	s_nop 0
	global_load_lds_dwordx4 v136, s[70:71]
	s_add_i32 m0, s69, 0x2000
	s_nop 0
	global_load_lds_dwordx4 v140, s[70:71]
	s_waitcnt vmcnt(6)
	s_setprio 1
	v_add_u32_e32 v157, 0x18000, v153
	s_barrier
	v_mfma_f32_16x16x32_bf16 v[48:51], v[218:221], v[186:189], v[48:51]
	ds_read_b128 v[158:161], v157
	v_mfma_f32_16x16x32_bf16 v[40:43], v[226:229], v[186:189], v[40:43]
	v_mfma_f32_16x16x32_bf16 v[32:35], v[218:221], v[194:197], v[32:35]
	ds_read_b128 v[174:177], v157 offset:1024
	v_mfma_f32_16x16x32_bf16 v[24:27], v[226:229], v[194:197], v[24:27]
	v_mfma_f32_16x16x32_bf16 v[16:19], v[218:221], v[202:205], v[16:19]
	ds_read_b128 v[178:181], v157 offset:2048
	v_mfma_f32_16x16x32_bf16 v[8:11], v[226:229], v[202:205], v[8:11]
	v_mfma_f32_16x16x32_bf16 v[4:7], v[218:221], v[210:213], v[4:7]
	ds_read_b128 v[182:185], v157 offset:3072
	v_mfma_f32_16x16x32_bf16 v[0:3], v[226:229], v[210:213], v[0:3]
	v_mfma_f32_16x16x32_bf16 v[48:51], v[222:225], v[190:193], v[48:51]
	ds_read_b128 v[186:189], v155 offset:32768
	v_mfma_f32_16x16x32_bf16 v[40:43], v[230:233], v[190:193], v[40:43]
	v_mfma_f32_16x16x32_bf16 v[32:35], v[222:225], v[198:201], v[32:35]
	ds_read_b128 v[194:197], v155 offset:34816
	v_mfma_f32_16x16x32_bf16 v[24:27], v[230:233], v[198:201], v[24:27]
	v_mfma_f32_16x16x32_bf16 v[16:19], v[222:225], v[206:209], v[16:19]
	ds_read_b128 v[202:205], v155 offset:36864
	v_mfma_f32_16x16x32_bf16 v[8:11], v[230:233], v[206:209], v[8:11]
	v_mfma_f32_16x16x32_bf16 v[4:7], v[222:225], v[214:217], v[4:7]
	ds_read_b128 v[210:213], v155 offset:38912
	v_mfma_f32_16x16x32_bf16 v[0:3], v[230:233], v[214:217], v[0:3]
	ds_read_b128 v[190:193], v155 offset:33792
	ds_read_b128 v[198:201], v155 offset:35840
	ds_read_b128 v[206:209], v155 offset:37888
	ds_read_b128 v[214:217], v155 offset:39936
	s_barrier
	s_setprio 0
	s_add_i32 s69, 0, 0x18000
	v_add_u32_e32 v157, s69, v153
	s_add_u32 s46, s46, 0x100000
	s_addc_u32 s47, s47, 0
	s_mov_b32 m0, s54
	s_nop 0
	global_load_lds_dwordx4 v134, s[46:47]
	s_mov_b32 m0, s55
	s_nop 0
	global_load_lds_dwordx4 v138, s[46:47]
	s_waitcnt lgkmcnt(8)
	s_waitcnt lgkmcnt(0)
	s_setprio 1
	v_add_u32_e32 v157, 0x1c000, v153
	s_barrier
; #define PG8_STAGE(bufoff, gbase, voff) do { _Pragma("unroll") for (int _i = 0; _i < 2; ++_i) \
;         __builtin_amdgcn_global_load_lds((const unsigned*)((const char*)(gbase) + (voff)[_i]), (LAS unsigned*)(lds + (bufoff) + ldsw + _i * 8192), 16, 0, 0); } while (0)
; #define PG8_LDA(dst, b, h) do { _Pragma("unroll") for (int m = 0; m < 4; ++m) _Pragma("unroll") for (int k = 0; k < 2; ++k) dst[m][k] = *(const LAS bf16x8*)(lds + PG8_SA(b, h) + aoff + m * 2048 + k * 1024); } while (0)
; #define PG8_LDB(dst, b, h) do { _Pragma("unroll") for (int n = 0; n < 2; ++n) _Pragma("unroll") for (int k = 0; k < 2; ++k) dst[n][k] = *(const LAS bf16x8*)(lds + PG8_SB(b, h) + boff + n * 2048 + k * 1024); } while (0)
; #define PG8_MMA(ai, bj, At, Bt) do { __builtin_amdgcn_s_setprio(1); _Pragma("unroll") for (int m = 0; m < 4; ++m) _Pragma("unroll") for (int n = 0; n < 2; ++n) _Pragma("unroll") for (int k = 0; k < 2; ++k) \
;         acc[ai][bj][m][n] = __builtin_amdgcn_mfma_f32_16x16x32_bf16(Bt[n][k], At[m][k], acc[ai][bj][m][n], 0, 0, 0); __builtin_amdgcn_s_setprio(0); } while (0)
;     __device__ __forceinline__ void operator()(const f32x4 (&acc)[2][2][4][2], const Unit& u, int wr, int wc, int fr, int fq) const {
;         const int row0 = u.orow + wr * 64 + fr;
;         bf16_t* base; size_t rstride, bjstride;
;         if (u.ocol < 6144) { const int sect = u.ocol >> 11, hh0 = (u.ocol & 2047) >> 7, b = u.orow >= SEQ ? 1 : 0;
;             base = qkv + (size_t)sect * MTOK * 2048 + ((size_t)(b * 16 + hh0) * SEQ + (row0 & (SEQ - 1))) * 128 + wc * 32 + 8 * fq; rstride = 128; bjstride = (size_t)SEQ * 128; }
;         else { base = proj2 + (size_t)row0 * NP2 + (u.ocol - 6144) + wc * 32 + 8 * fq; rstride = NP2; bjstride = HALF; }
; template <class Epi, class Job>
; __device__ __forceinline__ void gemm_phase(LAS unsigned char* lds, const Job& S, const Epi& E) {
;     ...
;             PG8_WAIT_L(8); PG8_BAR; PG8_WAIT_L(0); PG8_MMA(0, 0, At, B0); PG8_BAR; PG8_SCHED;
;             PG8_LDB(B1, 1, 1); PG8_STAGE(PG8_SB(1, 0), b3, voffB);
;             PG8_BAR; PG8_WAIT_L(0); PG8_MMA(0, 1, At, B1); PG8_BAR;
;             PG8_LDA(At, 1, 1); PG8_STAGE(PG8_SA(1, 0), a3, voffA);
;             PG8_BAR; PG8_WAIT_L(0); PG8_MMA(1, 0, At, B0); PG8_BAR; PG8_SCHED;
;             PG8_STAGE(PG8_SB(1, 1), b3 + hstepB, voffB);
;             PG8_WAIT_V(6); PG8_BAR; PG8_MMA(1, 1, At, B1); PG8_BAR;
	v_mfma_f32_16x16x32_bf16 v[124:127], v[158:161], v[186:189], v[124:127]
	ds_read_b128 v[218:221], v157
	v_mfma_f32_16x16x32_bf16 v[120:123], v[178:181], v[186:189], v[120:123]
	v_mfma_f32_16x16x32_bf16 v[112:115], v[158:161], v[194:197], v[112:115]
	ds_read_b128 v[222:225], v157 offset:1024
	v_mfma_f32_16x16x32_bf16 v[104:107], v[178:181], v[194:197], v[104:107]
	v_mfma_f32_16x16x32_bf16 v[100:103], v[158:161], v[202:205], v[100:103]
	ds_read_b128 v[226:229], v157 offset:2048
	v_mfma_f32_16x16x32_bf16 v[92:95], v[178:181], v[202:205], v[92:95]
	v_mfma_f32_16x16x32_bf16 v[84:87], v[158:161], v[210:213], v[84:87]
	ds_read_b128 v[230:233], v157 offset:3072
	v_mfma_f32_16x16x32_bf16 v[76:79], v[178:181], v[210:213], v[76:79]
	v_mfma_f32_16x16x32_bf16 v[124:127], v[174:177], v[190:193], v[124:127]
	v_mfma_f32_16x16x32_bf16 v[120:123], v[182:185], v[190:193], v[120:123]
	v_mfma_f32_16x16x32_bf16 v[112:115], v[174:177], v[198:201], v[112:115]
	v_mfma_f32_16x16x32_bf16 v[104:107], v[182:185], v[198:201], v[104:107]
	v_mfma_f32_16x16x32_bf16 v[100:103], v[174:177], v[206:209], v[100:103]
	v_mfma_f32_16x16x32_bf16 v[92:95], v[182:185], v[206:209], v[92:95]
	v_mfma_f32_16x16x32_bf16 v[84:87], v[174:177], v[214:217], v[84:87]
	v_mfma_f32_16x16x32_bf16 v[76:79], v[182:185], v[214:217], v[76:79]
	s_barrier
	s_setprio 0
	s_add_i32 s46, 0, 0x1c000
	s_add_i32 s47, s69, s49
	v_add_u32_e32 v157, s46, v153
	s_add_u32 s98, s36, s10
	s_addc_u32 s99, s37, s11
	s_mov_b32 m0, s47
	s_nop 0
	global_load_lds_dwordx4 v136, s[98:99]
	s_add_i32 m0, s47, 0x2000
	s_nop 0
	global_load_lds_dwordx4 v140, s[98:99]
	s_waitcnt lgkmcnt(0)
	s_setprio 1
	s_barrier
	v_mfma_f32_16x16x32_bf16 v[116:119], v[218:221], v[186:189], v[116:119]
	v_mfma_f32_16x16x32_bf16 v[108:111], v[226:229], v[186:189], v[108:111]
	v_mfma_f32_16x16x32_bf16 v[96:99], v[218:221], v[194:197], v[96:99]
	v_mfma_f32_16x16x32_bf16 v[88:91], v[226:229], v[194:197], v[88:91]
	v_mfma_f32_16x16x32_bf16 v[80:83], v[218:221], v[202:205], v[80:83]
	v_mfma_f32_16x16x32_bf16 v[72:75], v[226:229], v[202:205], v[72:75]
	v_mfma_f32_16x16x32_bf16 v[68:71], v[218:221], v[210:213], v[68:71]
	v_mfma_f32_16x16x32_bf16 v[64:67], v[226:229], v[210:213], v[64:67]
	v_mfma_f32_16x16x32_bf16 v[116:119], v[222:225], v[190:193], v[116:119]
	ds_read_b128 v[186:189], v155 offset:49152
	v_mfma_f32_16x16x32_bf16 v[108:111], v[230:233], v[190:193], v[108:111]
	v_mfma_f32_16x16x32_bf16 v[96:99], v[222:225], v[198:201], v[96:99]
	ds_read_b128 v[194:197], v155 offset:51200
	v_mfma_f32_16x16x32_bf16 v[88:91], v[230:233], v[198:201], v[88:91]
	v_mfma_f32_16x16x32_bf16 v[80:83], v[222:225], v[206:209], v[80:83]
	ds_read_b128 v[202:205], v155 offset:53248
	v_mfma_f32_16x16x32_bf16 v[72:75], v[230:233], v[206:209], v[72:75]
	v_mfma_f32_16x16x32_bf16 v[68:71], v[222:225], v[214:217], v[68:71]
	ds_read_b128 v[210:213], v155 offset:55296
	v_mfma_f32_16x16x32_bf16 v[64:67], v[230:233], v[214:217], v[64:67]
	ds_read_b128 v[190:193], v155 offset:50176
	ds_read_b128 v[198:201], v155 offset:52224
	ds_read_b128 v[206:209], v155 offset:54272
	ds_read_b128 v[214:217], v155 offset:56320
	s_barrier
	s_setprio 0
	s_mov_b32 m0, s56
	s_add_u32 s100, s100, s10
	s_addc_u32 s101, s101, s11
	global_load_lds_dwordx4 v134, s[100:101]
	s_mov_b32 m0, s57
	s_nop 0
	global_load_lds_dwordx4 v138, s[100:101]
	s_waitcnt vmcnt(8)
	s_waitcnt lgkmcnt(0)
	s_setprio 1
	s_barrier
	v_mfma_f32_16x16x32_bf16 v[60:63], v[158:161], v[186:189], v[60:63]
	v_mfma_f32_16x16x32_bf16 v[56:59], v[178:181], v[186:189], v[56:59]
	v_mfma_f32_16x16x32_bf16 v[52:55], v[158:161], v[194:197], v[52:55]
	v_mfma_f32_16x16x32_bf16 v[44:47], v[178:181], v[194:197], v[44:47]
	v_mfma_f32_16x16x32_bf16 v[36:39], v[158:161], v[202:205], v[36:39]
	v_mfma_f32_16x16x32_bf16 v[28:31], v[178:181], v[202:205], v[28:31]
	v_mfma_f32_16x16x32_bf16 v[20:23], v[158:161], v[210:213], v[20:23]
	v_mfma_f32_16x16x32_bf16 v[12:15], v[178:181], v[210:213], v[12:15]
	v_mfma_f32_16x16x32_bf16 v[60:63], v[174:177], v[190:193], v[60:63]
	v_mfma_f32_16x16x32_bf16 v[56:59], v[182:185], v[190:193], v[56:59]
	v_mfma_f32_16x16x32_bf16 v[52:55], v[174:177], v[198:201], v[52:55]
	v_mfma_f32_16x16x32_bf16 v[44:47], v[182:185], v[198:201], v[44:47]
	v_mfma_f32_16x16x32_bf16 v[36:39], v[174:177], v[206:209], v[36:39]
	v_mfma_f32_16x16x32_bf16 v[28:31], v[182:185], v[206:209], v[28:31]
	v_mfma_f32_16x16x32_bf16 v[20:23], v[174:177], v[214:217], v[20:23]
	v_mfma_f32_16x16x32_bf16 v[12:15], v[182:185], v[214:217], v[12:15]
	s_barrier
	s_setprio 0
	s_add_u32 s36, s36, 0x100080
	s_addc_u32 s37, s37, 0
	s_add_i32 s46, s46, s49
	s_mov_b32 m0, s46
	s_nop 0
	global_load_lds_dwordx4 v136, s[36:37]
	s_add_i32 m0, s46, 0x2000
	s_nop 0
	global_load_lds_dwordx4 v140, s[36:37]
	s_waitcnt vmcnt(6)
	s_setprio 1
	s_barrier
	v_mfma_f32_16x16x32_bf16 v[48:51], v[218:221], v[186:189], v[48:51]
	ds_read_b128 v[158:161], v154
	v_mfma_f32_16x16x32_bf16 v[40:43], v[226:229], v[186:189], v[40:43]
	v_mfma_f32_16x16x32_bf16 v[32:35], v[218:221], v[194:197], v[32:35]
	ds_read_b128 v[174:177], v154 offset:1024
	v_mfma_f32_16x16x32_bf16 v[24:27], v[226:229], v[194:197], v[24:27]
	v_mfma_f32_16x16x32_bf16 v[16:19], v[218:221], v[202:205], v[16:19]
	ds_read_b128 v[178:181], v154 offset:2048
	v_mfma_f32_16x16x32_bf16 v[8:11], v[226:229], v[202:205], v[8:11]
	v_mfma_f32_16x16x32_bf16 v[4:7], v[218:221], v[210:213], v[4:7]
	ds_read_b128 v[182:185], v154 offset:3072
	v_mfma_f32_16x16x32_bf16 v[0:3], v[226:229], v[210:213], v[0:3]
	v_mfma_f32_16x16x32_bf16 v[48:51], v[222:225], v[190:193], v[48:51]
	ds_read_b128 v[186:189], v155
	v_mfma_f32_16x16x32_bf16 v[40:43], v[230:233], v[190:193], v[40:43]
	v_mfma_f32_16x16x32_bf16 v[32:35], v[222:225], v[198:201], v[32:35]
	ds_read_b128 v[194:197], v155 offset:2048
	v_mfma_f32_16x16x32_bf16 v[24:27], v[230:233], v[198:201], v[24:27]
	v_mfma_f32_16x16x32_bf16 v[16:19], v[222:225], v[206:209], v[16:19]
	ds_read_b128 v[202:205], v155 offset:4096
	v_mfma_f32_16x16x32_bf16 v[8:11], v[230:233], v[206:209], v[8:11]
	v_mfma_f32_16x16x32_bf16 v[4:7], v[222:225], v[214:217], v[4:7]
	ds_read_b128 v[210:213], v155 offset:6144
	v_mfma_f32_16x16x32_bf16 v[0:3], v[230:233], v[214:217], v[0:3]
	ds_read_b128 v[190:193], v155 offset:1024
	ds_read_b128 v[198:201], v155 offset:3072
	ds_read_b128 v[206:209], v155 offset:5120
	ds_read_b128 v[214:217], v155 offset:7168
	s_barrier
	s_setprio 0
	s_add_i32 s68, s68, 2
	s_add_u32 s28, s28, 0x100
	s_addc_u32 s29, s29, 0
	s_add_u32 s27, s27, 0x100
	s_addc_u32 s67, s67, 0
	s_cmp_gt_u32 s68, 61
	s_cbranch_scc0 .LBB0_186
	s_waitcnt lgkmcnt(0)
	v_add_u32_e32 v157, s66, v131
	s_cmpk_gt_i32 s26, 0x17ff
	s_mov_b64 s[28:29], -1
	s_cbranch_scc0 .LBB0_189
	v_mov_b64_e32 v[150:151], s[20:21]
	v_mad_i64_i32 v[150:151], s[28:29], v157, s62, v[150:151]
	s_mov_b32 s27, s9
	v_lshl_add_u64 v[150:151], s[26:27], 1, v[150:151]
	v_lshl_add_u64 v[150:151], v[150:151], 0, s[12:13]
	s_mov_b64 s[28:29], 0

; #define PG8_STAGE(bufoff, gbase, voff) do { _Pragma("unroll") for (int _i = 0; _i < 2; ++_i) \
;         __builtin_amdgcn_global_load_lds((const unsigned*)((const char*)(gbase) + (voff)[_i]), (LAS unsigned*)(lds + (bufoff) + ldsw + _i * 8192), 16, 0, 0); } while (0)
; #define PG8_LDA(dst, b, h) do { _Pragma("unroll") for (int m = 0; m < 4; ++m) _Pragma("unroll") for (int k = 0; k < 2; ++k) dst[m][k] = *(const LAS bf16x8*)(lds + PG8_SA(b, h) + aoff + m * 2048 + k * 1024); } while (0)
; #define PG8_LDB(dst, b, h) do { _Pragma("unroll") for (int n = 0; n < 2; ++n) _Pragma("unroll") for (int k = 0; k < 2; ++k) dst[n][k] = *(const LAS bf16x8*)(lds + PG8_SB(b, h) + boff + n * 2048 + k * 1024); } while (0)
; #define PG8_WAIT_L(n) asm volatile("s_waitcnt lgkmcnt(" #n ")" ::: "memory")
; #define PG8_BAR __builtin_amdgcn_s_barrier()
; #define PG8_SCHED __builtin_amdgcn_sched_barrier(0)
; template <class Epi, class Job>
; __device__ __forceinline__ void gemm_phase(LAS unsigned char* lds, const Job& S, const Epi& E) {
;     ...
;         const bool has_next = S.next(ui + 1, nxt);
;         const char* nA = has_next ? nxt.a : cA; const char* nB = has_next ? nxt.b : cB;
;         for (int t = 0; t < nt; t += 2) {
;             const bool last = (t == nt - 2);
;             const char* a1 = cA + (size_t)(t + 1) * kstep;
;             const char* a2 = last ? nA : cA + (size_t)(t + 2) * kstep; const char* b2 = last ? nB : cB + (size_t)(t + 2) * kstep;
;             const char* a3 = a2 + kstep; const char* b3 = b2 + kstep;
;             PG8_LDB(B0, 0, 0); PG8_SCHED; PG8_LDA(At, 0, 0); PG8_STAGE(PG8_SA(1, 1), a1 + hstepA, voffA);
;             PG8_WAIT_L(8); PG8_BAR; PG8_WAIT_L(0); PG8_MMA(0, 0, At, B0); PG8_BAR; PG8_SCHED;
;             PG8_LDB(B1, 0, 1); PG8_STAGE(PG8_SB(0, 0), b2, voffB);
;             PG8_BAR; PG8_WAIT_L(0); PG8_MMA(0, 1, At, B1); PG8_BAR;
;             PG8_LDA(At, 0, 1); PG8_STAGE(PG8_SA(0, 0), a2, voffA);
;             PG8_BAR; PG8_WAIT_L(0); PG8_MMA(1, 0, At, B0); PG8_BAR; PG8_SCHED;
;     ...
; #pragma unroll
;         for (int a = 0; a < 2; ++a)
; #pragma unroll
;             for (int b = 0; b < 2; ++b)
; #pragma unroll
;                 for (int m = 0; m < 4; ++m)
; #pragma unroll
;                     for (int n = 0; n < 2; ++n) acc[a][b][m][n] = (f32x4){0.f, 0.f, 0.f, 0.f};
;         cur = nxt; cA = nA; cB = nB; ++ui;
.LBB0_456:
	s_add_u32 s36, s36, 0x100080
	s_addc_u32 s37, s37, 0
	s_add_u32 s79, s46, 0x100
	v_mov_b32_e32 v0, 0
	s_addc_u32 s80, s47, 0
	s_mov_b32 s81, -2
	v_mov_b32_e32 v1, v0
	v_mov_b32_e32 v2, v0
	v_mov_b32_e32 v3, v0
	v_mov_b32_e32 v4, v0
	v_mov_b32_e32 v5, v0
	v_mov_b32_e32 v6, v0
	v_mov_b32_e32 v7, v0
	v_mov_b32_e32 v8, v0
	v_mov_b32_e32 v9, v0
	v_mov_b32_e32 v10, v0
	v_mov_b32_e32 v11, v0
	v_mov_b32_e32 v16, v0
	v_mov_b32_e32 v17, v0
	v_mov_b32_e32 v18, v0
	v_mov_b32_e32 v19, v0
	v_mov_b32_e32 v24, v0
	v_mov_b32_e32 v25, v0
	v_mov_b32_e32 v26, v0
	v_mov_b32_e32 v27, v0
	v_mov_b32_e32 v32, v0
	v_mov_b32_e32 v33, v0
	v_mov_b32_e32 v34, v0
	v_mov_b32_e32 v35, v0
	v_mov_b32_e32 v40, v0
	v_mov_b32_e32 v41, v0
	v_mov_b32_e32 v42, v0
	v_mov_b32_e32 v43, v0
	v_mov_b32_e32 v48, v0
	v_mov_b32_e32 v49, v0
	v_mov_b32_e32 v50, v0
	v_mov_b32_e32 v51, v0
	v_mov_b32_e32 v12, v0
	v_mov_b32_e32 v13, v0
	v_mov_b32_e32 v14, v0
	v_mov_b32_e32 v15, v0
	v_mov_b32_e32 v20, v0
	v_mov_b32_e32 v21, v0
	v_mov_b32_e32 v22, v0
	v_mov_b32_e32 v23, v0
	v_mov_b32_e32 v28, v0
	v_mov_b32_e32 v29, v0
	v_mov_b32_e32 v30, v0
	v_mov_b32_e32 v31, v0
	v_mov_b32_e32 v36, v0
	v_mov_b32_e32 v37, v0
	v_mov_b32_e32 v38, v0
	v_mov_b32_e32 v39, v0
	v_mov_b32_e32 v44, v0
	v_mov_b32_e32 v45, v0
	v_mov_b32_e32 v46, v0
	v_mov_b32_e32 v47, v0
	v_mov_b32_e32 v52, v0
	v_mov_b32_e32 v53, v0
	v_mov_b32_e32 v54, v0
	v_mov_b32_e32 v55, v0
	v_mov_b32_e32 v56, v0
	v_mov_b32_e32 v57, v0
	v_mov_b32_e32 v58, v0
	v_mov_b32_e32 v59, v0
	v_mov_b32_e32 v60, v0
	v_mov_b32_e32 v61, v0
	v_mov_b32_e32 v62, v0
	v_mov_b32_e32 v63, v0
	v_mov_b32_e32 v64, v0
	v_mov_b32_e32 v65, v0
	v_mov_b32_e32 v66, v0
	v_mov_b32_e32 v67, v0
	v_mov_b32_e32 v68, v0
	v_mov_b32_e32 v69, v0
	v_mov_b32_e32 v70, v0
	v_mov_b32_e32 v71, v0
	v_mov_b32_e32 v72, v0
	v_mov_b32_e32 v73, v0
	v_mov_b32_e32 v74, v0
	v_mov_b32_e32 v75, v0
	v_mov_b32_e32 v80, v0
	v_mov_b32_e32 v81, v0
	v_mov_b32_e32 v82, v0
	v_mov_b32_e32 v83, v0
	v_mov_b32_e32 v88, v0
	v_mov_b32_e32 v89, v0
	v_mov_b32_e32 v90, v0
	v_mov_b32_e32 v91, v0
	v_mov_b32_e32 v96, v0
	v_mov_b32_e32 v97, v0
	v_mov_b32_e32 v98, v0
	v_mov_b32_e32 v99, v0
	v_mov_b32_e32 v104, v0
	v_mov_b32_e32 v105, v0
	v_mov_b32_e32 v106, v0
	v_mov_b32_e32 v107, v0
	v_mov_b32_e32 v112, v0
	v_mov_b32_e32 v113, v0
	v_mov_b32_e32 v114, v0
	v_mov_b32_e32 v115, v0
	v_mov_b32_e32 v76, v0
	v_mov_b32_e32 v77, v0
	v_mov_b32_e32 v78, v0
	v_mov_b32_e32 v79, v0
	v_mov_b32_e32 v84, v0
	v_mov_b32_e32 v85, v0
	v_mov_b32_e32 v86, v0
	v_mov_b32_e32 v87, v0
	v_mov_b32_e32 v92, v0
	v_mov_b32_e32 v93, v0
	v_mov_b32_e32 v94, v0
	v_mov_b32_e32 v95, v0
	v_mov_b32_e32 v100, v0
	v_mov_b32_e32 v101, v0
	v_mov_b32_e32 v102, v0
	v_mov_b32_e32 v103, v0
	v_mov_b32_e32 v108, v0
	v_mov_b32_e32 v109, v0
	v_mov_b32_e32 v110, v0
	v_mov_b32_e32 v111, v0
	v_mov_b32_e32 v116, v0
	v_mov_b32_e32 v117, v0
	v_mov_b32_e32 v118, v0
	v_mov_b32_e32 v119, v0
	v_mov_b32_e32 v120, v0
	v_mov_b32_e32 v121, v0
	v_mov_b32_e32 v122, v0
	v_mov_b32_e32 v123, v0
	v_mov_b32_e32 v124, v0
	v_mov_b32_e32 v125, v0
	v_mov_b32_e32 v126, v0
	v_mov_b32_e32 v127, v0
	ds_read_b128 v[154:157], v150
	ds_read_b128 v[158:161], v150 offset:1024
	ds_read_b128 v[162:165], v150 offset:2048
	ds_read_b128 v[166:169], v150 offset:3072
	ds_read_b128 v[170:173], v151
	ds_read_b128 v[178:181], v151 offset:2048
	ds_read_b128 v[186:189], v151 offset:4096
	ds_read_b128 v[194:197], v151 offset:6144
	ds_read_b128 v[174:177], v151 offset:1024
	ds_read_b128 v[182:185], v151 offset:3072
	ds_read_b128 v[190:193], v151 offset:5120
	ds_read_b128 v[198:201], v151 offset:7168
.LBB0_457:
	s_add_i32 m0, s57, 0xc000
	s_nop 0
	global_load_lds_dwordx4 v132, s[36:37]
	s_add_i32 m0, s57, 0xe000
	s_nop 0
	global_load_lds_dwordx4 v142, s[36:37]
	s_add_u32 s46, s36, 0xfff00080
	s_addc_u32 s47, s37, -1
	s_cmp_eq_u32 s81, 60
	s_cselect_b32 s49, s29, s47
	s_cselect_b32 s48, s28, s46
	s_cselect_b32 s47, s31, s80
	s_cselect_b32 s46, s30, s79
	s_waitcnt lgkmcnt(8)
	s_waitcnt lgkmcnt(0)
	s_setprio 1
	s_barrier
	v_mfma_f32_16x16x32_bf16 v[124:127], v[154:157], v[170:173], v[124:127]
	ds_read_b128 v[202:205], v152
	v_mfma_f32_16x16x32_bf16 v[120:123], v[162:165], v[170:173], v[120:123]
	v_mfma_f32_16x16x32_bf16 v[116:119], v[154:157], v[178:181], v[116:119]
	ds_read_b128 v[206:209], v152 offset:1024
	v_mfma_f32_16x16x32_bf16 v[108:111], v[162:165], v[178:181], v[108:111]
	v_mfma_f32_16x16x32_bf16 v[100:103], v[154:157], v[186:189], v[100:103]
	ds_read_b128 v[210:213], v152 offset:2048
	v_mfma_f32_16x16x32_bf16 v[92:95], v[162:165], v[186:189], v[92:95]
	v_mfma_f32_16x16x32_bf16 v[84:87], v[154:157], v[194:197], v[84:87]
	ds_read_b128 v[214:217], v152 offset:3072
	v_mfma_f32_16x16x32_bf16 v[76:79], v[162:165], v[194:197], v[76:79]
	v_mfma_f32_16x16x32_bf16 v[124:127], v[158:161], v[174:177], v[124:127]
	v_mfma_f32_16x16x32_bf16 v[120:123], v[166:169], v[174:177], v[120:123]
	v_mfma_f32_16x16x32_bf16 v[116:119], v[158:161], v[182:185], v[116:119]
	v_mfma_f32_16x16x32_bf16 v[108:111], v[166:169], v[182:185], v[108:111]
	v_mfma_f32_16x16x32_bf16 v[100:103], v[158:161], v[190:193], v[100:103]
	v_mfma_f32_16x16x32_bf16 v[92:95], v[166:169], v[190:193], v[92:95]
	v_mfma_f32_16x16x32_bf16 v[84:87], v[158:161], v[198:201], v[84:87]
	v_mfma_f32_16x16x32_bf16 v[76:79], v[166:169], v[198:201], v[76:79]
	s_barrier
	s_setprio 0
	s_add_i32 s82, s66, s56
	s_mov_b32 m0, s82
	s_nop 0
	global_load_lds_dwordx4 v136, s[46:47]
	s_add_i32 m0, s82, 0x2000
	s_nop 0
	global_load_lds_dwordx4 v140, s[46:47]
	s_waitcnt lgkmcnt(0)
	s_setprio 1
	s_barrier
; #define PG8_STAGE(bufoff, gbase, voff) do { _Pragma("unroll") for (int _i = 0; _i < 2; ++_i) \
;         __builtin_amdgcn_global_load_lds((const unsigned*)((const char*)(gbase) + (voff)[_i]), (LAS unsigned*)(lds + (bufoff) + ldsw + _i * 8192), 16, 0, 0); } while (0)
; #define PG8_LDA(dst, b, h) do { _Pragma("unroll") for (int m = 0; m < 4; ++m) _Pragma("unroll") for (int k = 0; k < 2; ++k) dst[m][k] = *(const LAS bf16x8*)(lds + PG8_SA(b, h) + aoff + m * 2048 + k * 1024); } while (0)
; #define PG8_LDB(dst, b, h) do { _Pragma("unroll") for (int n = 0; n < 2; ++n) _Pragma("unroll") for (int k = 0; k < 2; ++k) dst[n][k] = *(const LAS bf16x8*)(lds + PG8_SB(b, h) + boff + n * 2048 + k * 1024); } while (0)
; #define PG8_MMA(ai, bj, At, Bt) do { __builtin_amdgcn_s_setprio(1); _Pragma("unroll") for (int m = 0; m < 4; ++m) _Pragma("unroll") for (int n = 0; n < 2; ++n) _Pragma("unroll") for (int k = 0; k < 2; ++k) \
;         acc[ai][bj][m][n] = __builtin_amdgcn_mfma_f32_16x16x32_bf16(Bt[n][k], At[m][k], acc[ai][bj][m][n], 0, 0, 0); __builtin_amdgcn_s_setprio(0); } while (0)
; #define PG8_WAIT_V(n) asm volatile("s_waitcnt vmcnt(" #n ")" ::: "memory")
; #define PG8_WAIT_L(n) asm volatile("s_waitcnt lgkmcnt(" #n ")" ::: "memory")
; #define PG8_BAR __builtin_amdgcn_s_barrier()
; #define PG8_SCHED __builtin_amdgcn_sched_barrier(0)
; template <class Epi, class Job>
; __device__ __forceinline__ void gemm_phase(LAS unsigned char* lds, const Job& S, const Epi& E) {
;     ...
;             PG8_LDB(B1, 0, 1); PG8_STAGE(PG8_SB(0, 0), b2, voffB);
;             PG8_BAR; PG8_WAIT_L(0); PG8_MMA(0, 1, At, B1); PG8_BAR;
;             PG8_LDA(At, 0, 1); PG8_STAGE(PG8_SA(0, 0), a2, voffA);
;             PG8_BAR; PG8_WAIT_L(0); PG8_MMA(1, 0, At, B0); PG8_BAR; PG8_SCHED;
;             PG8_STAGE(PG8_SB(0, 1), b2 + hstepB, voffB);
;             PG8_WAIT_V(6); PG8_BAR; PG8_MMA(1, 1, At, B1); PG8_BAR;
;             PG8_LDB(B0, 1, 0); PG8_SCHED; PG8_LDA(At, 1, 0); PG8_STAGE(PG8_SA(0, 1), a2 + hstepA, voffA);
;             PG8_WAIT_L(8); PG8_BAR; PG8_WAIT_L(0); PG8_MMA(0, 0, At, B0); PG8_BAR; PG8_SCHED;
	v_mfma_f32_16x16x32_bf16 v[112:115], v[202:205], v[170:173], v[112:115]
	v_mfma_f32_16x16x32_bf16 v[104:107], v[210:213], v[170:173], v[104:107]
	v_mfma_f32_16x16x32_bf16 v[96:99], v[202:205], v[178:181], v[96:99]
	v_mfma_f32_16x16x32_bf16 v[88:91], v[210:213], v[178:181], v[88:91]
	v_mfma_f32_16x16x32_bf16 v[80:83], v[202:205], v[186:189], v[80:83]
	v_mfma_f32_16x16x32_bf16 v[72:75], v[210:213], v[186:189], v[72:75]
	v_mfma_f32_16x16x32_bf16 v[68:71], v[202:205], v[194:197], v[68:71]
	v_mfma_f32_16x16x32_bf16 v[64:67], v[210:213], v[194:197], v[64:67]
	v_mfma_f32_16x16x32_bf16 v[112:115], v[206:209], v[174:177], v[112:115]
	ds_read_b128 v[170:173], v151 offset:16384
	v_mfma_f32_16x16x32_bf16 v[104:107], v[214:217], v[174:177], v[104:107]
	v_mfma_f32_16x16x32_bf16 v[96:99], v[206:209], v[182:185], v[96:99]
	ds_read_b128 v[178:181], v151 offset:18432
	v_mfma_f32_16x16x32_bf16 v[88:91], v[214:217], v[182:185], v[88:91]
	v_mfma_f32_16x16x32_bf16 v[80:83], v[206:209], v[190:193], v[80:83]
	ds_read_b128 v[186:189], v151 offset:20480
	v_mfma_f32_16x16x32_bf16 v[72:75], v[214:217], v[190:193], v[72:75]
	v_mfma_f32_16x16x32_bf16 v[68:71], v[206:209], v[198:201], v[68:71]
	ds_read_b128 v[194:197], v151 offset:22528
	v_mfma_f32_16x16x32_bf16 v[64:67], v[214:217], v[198:201], v[64:67]
	ds_read_b128 v[174:177], v151 offset:17408
	ds_read_b128 v[182:185], v151 offset:19456
	ds_read_b128 v[190:193], v151 offset:21504
	ds_read_b128 v[198:201], v151 offset:23552
	s_barrier
	s_setprio 0
	s_mov_b32 m0, s57
	s_mov_b64 s[100:101], s[48:49]
	global_load_lds_dwordx4 v134, s[48:49]
	s_mov_b32 m0, s58
	s_nop 0
	global_load_lds_dwordx4 v138, s[48:49]
	s_waitcnt vmcnt(8)
	s_waitcnt lgkmcnt(0)
	s_setprio 1
	s_barrier
	v_mfma_f32_16x16x32_bf16 v[60:63], v[154:157], v[170:173], v[60:63]
	v_mfma_f32_16x16x32_bf16 v[56:59], v[162:165], v[170:173], v[56:59]
	v_mfma_f32_16x16x32_bf16 v[52:55], v[154:157], v[178:181], v[52:55]
	v_mfma_f32_16x16x32_bf16 v[44:47], v[162:165], v[178:181], v[44:47]
	v_mfma_f32_16x16x32_bf16 v[36:39], v[154:157], v[186:189], v[36:39]
	v_mfma_f32_16x16x32_bf16 v[28:31], v[162:165], v[186:189], v[28:31]
	v_mfma_f32_16x16x32_bf16 v[20:23], v[154:157], v[194:197], v[20:23]
	v_mfma_f32_16x16x32_bf16 v[12:15], v[162:165], v[194:197], v[12:15]
	v_mfma_f32_16x16x32_bf16 v[60:63], v[158:161], v[174:177], v[60:63]
	v_mfma_f32_16x16x32_bf16 v[56:59], v[166:169], v[174:177], v[56:59]
	v_mfma_f32_16x16x32_bf16 v[52:55], v[158:161], v[182:185], v[52:55]
	v_mfma_f32_16x16x32_bf16 v[44:47], v[166:169], v[182:185], v[44:47]
	v_mfma_f32_16x16x32_bf16 v[36:39], v[158:161], v[190:193], v[36:39]
	v_mfma_f32_16x16x32_bf16 v[28:31], v[166:169], v[190:193], v[28:31]
	v_mfma_f32_16x16x32_bf16 v[20:23], v[158:161], v[198:201], v[20:23]
	v_mfma_f32_16x16x32_bf16 v[12:15], v[166:169], v[198:201], v[12:15]
	s_barrier
	s_setprio 0
	s_add_u32 s82, s46, 0x100000
	s_addc_u32 s83, s47, 0
	s_add_i32 s84, s67, s56
	s_mov_b32 m0, s84
	s_nop 0
	global_load_lds_dwordx4 v136, s[82:83]
	s_add_i32 m0, s84, 0x2000
	s_nop 0
	global_load_lds_dwordx4 v140, s[82:83]
	s_waitcnt vmcnt(6)
	s_setprio 1
	v_add_u32_e32 v153, 0x18000, v148
	s_barrier
	v_mfma_f32_16x16x32_bf16 v[48:51], v[202:205], v[170:173], v[48:51]
	ds_read_b128 v[154:157], v153
	v_mfma_f32_16x16x32_bf16 v[40:43], v[210:213], v[170:173], v[40:43]
	v_mfma_f32_16x16x32_bf16 v[32:35], v[202:205], v[178:181], v[32:35]
	ds_read_b128 v[158:161], v153 offset:1024
	v_mfma_f32_16x16x32_bf16 v[24:27], v[210:213], v[178:181], v[24:27]
	v_mfma_f32_16x16x32_bf16 v[16:19], v[202:205], v[186:189], v[16:19]
	ds_read_b128 v[162:165], v153 offset:2048
	v_mfma_f32_16x16x32_bf16 v[8:11], v[210:213], v[186:189], v[8:11]
	v_mfma_f32_16x16x32_bf16 v[4:7], v[202:205], v[194:197], v[4:7]
	ds_read_b128 v[166:169], v153 offset:3072
	v_mfma_f32_16x16x32_bf16 v[0:3], v[210:213], v[194:197], v[0:3]
	v_mfma_f32_16x16x32_bf16 v[48:51], v[206:209], v[174:177], v[48:51]
	ds_read_b128 v[170:173], v151 offset:32768
	v_mfma_f32_16x16x32_bf16 v[40:43], v[214:217], v[174:177], v[40:43]
	v_mfma_f32_16x16x32_bf16 v[32:35], v[206:209], v[182:185], v[32:35]
	ds_read_b128 v[178:181], v151 offset:34816
	v_mfma_f32_16x16x32_bf16 v[24:27], v[214:217], v[182:185], v[24:27]
	v_mfma_f32_16x16x32_bf16 v[16:19], v[206:209], v[190:193], v[16:19]
	ds_read_b128 v[186:189], v151 offset:36864
	v_mfma_f32_16x16x32_bf16 v[8:11], v[214:217], v[190:193], v[8:11]
	v_mfma_f32_16x16x32_bf16 v[4:7], v[206:209], v[198:201], v[4:7]
	ds_read_b128 v[194:197], v151 offset:38912
	v_mfma_f32_16x16x32_bf16 v[0:3], v[214:217], v[198:201], v[0:3]
	ds_read_b128 v[174:177], v151 offset:33792
	ds_read_b128 v[182:185], v151 offset:35840
	ds_read_b128 v[190:193], v151 offset:37888
	ds_read_b128 v[198:201], v151 offset:39936
	s_barrier
	s_setprio 0
	s_add_i32 s82, 0, 0x18000
	v_add_u32_e32 v153, s82, v148
	s_add_u32 s48, s48, 0x100000
	s_addc_u32 s49, s49, 0
	s_mov_b32 m0, s59
	s_nop 0
	global_load_lds_dwordx4 v134, s[48:49]
	s_mov_b32 m0, s60
	s_nop 0
	global_load_lds_dwordx4 v138, s[48:49]
	s_waitcnt lgkmcnt(8)
	s_waitcnt lgkmcnt(0)
	s_setprio 1
	v_add_u32_e32 v153, 0x1c000, v148
	s_barrier
; #define PG8_STAGE(bufoff, gbase, voff) do { _Pragma("unroll") for (int _i = 0; _i < 2; ++_i) \
;         __builtin_amdgcn_global_load_lds((const unsigned*)((const char*)(gbase) + (voff)[_i]), (LAS unsigned*)(lds + (bufoff) + ldsw + _i * 8192), 16, 0, 0); } while (0)
; #define PG8_LDA(dst, b, h) do { _Pragma("unroll") for (int m = 0; m < 4; ++m) _Pragma("unroll") for (int k = 0; k < 2; ++k) dst[m][k] = *(const LAS bf16x8*)(lds + PG8_SA(b, h) + aoff + m * 2048 + k * 1024); } while (0)
; #define PG8_LDB(dst, b, h) do { _Pragma("unroll") for (int n = 0; n < 2; ++n) _Pragma("unroll") for (int k = 0; k < 2; ++k) dst[n][k] = *(const LAS bf16x8*)(lds + PG8_SB(b, h) + boff + n * 2048 + k * 1024); } while (0)
; #define PG8_MMA(ai, bj, At, Bt) do { __builtin_amdgcn_s_setprio(1); _Pragma("unroll") for (int m = 0; m < 4; ++m) _Pragma("unroll") for (int n = 0; n < 2; ++n) _Pragma("unroll") for (int k = 0; k < 2; ++k) \
;         acc[ai][bj][m][n] = __builtin_amdgcn_mfma_f32_16x16x32_bf16(Bt[n][k], At[m][k], acc[ai][bj][m][n], 0, 0, 0); __builtin_amdgcn_s_setprio(0); } while (0)
; #define PG8_WAIT_V(n) asm volatile("s_waitcnt vmcnt(" #n ")" ::: "memory")
; #define PG8_WAIT_L(n) asm volatile("s_waitcnt lgkmcnt(" #n ")" ::: "memory")
; #define PG8_BAR __builtin_amdgcn_s_barrier()
; #define PG8_SCHED __builtin_amdgcn_sched_barrier(0)
; template <class Epi, class Job>
; __device__ __forceinline__ void gemm_phase(LAS unsigned char* lds, const Job& S, const Epi& E) {
;     ...
;             PG8_WAIT_L(8); PG8_BAR; PG8_WAIT_L(0); PG8_MMA(0, 0, At, B0); PG8_BAR; PG8_SCHED;
;             PG8_LDB(B1, 1, 1); PG8_STAGE(PG8_SB(1, 0), b3, voffB);
;             PG8_BAR; PG8_WAIT_L(0); PG8_MMA(0, 1, At, B1); PG8_BAR;
;             PG8_LDA(At, 1, 1); PG8_STAGE(PG8_SA(1, 0), a3, voffA);
;             PG8_BAR; PG8_WAIT_L(0); PG8_MMA(1, 0, At, B0); PG8_BAR; PG8_SCHED;
;             PG8_STAGE(PG8_SB(1, 1), b3 + hstepB, voffB);
;             PG8_WAIT_V(6); PG8_BAR; PG8_MMA(1, 1, At, B1); PG8_BAR;
	v_mfma_f32_16x16x32_bf16 v[124:127], v[154:157], v[170:173], v[124:127]
	ds_read_b128 v[202:205], v153
	v_mfma_f32_16x16x32_bf16 v[120:123], v[162:165], v[170:173], v[120:123]
	v_mfma_f32_16x16x32_bf16 v[116:119], v[154:157], v[178:181], v[116:119]
	ds_read_b128 v[206:209], v153 offset:1024
	v_mfma_f32_16x16x32_bf16 v[108:111], v[162:165], v[178:181], v[108:111]
	v_mfma_f32_16x16x32_bf16 v[100:103], v[154:157], v[186:189], v[100:103]
	ds_read_b128 v[210:213], v153 offset:2048
	v_mfma_f32_16x16x32_bf16 v[92:95], v[162:165], v[186:189], v[92:95]
	v_mfma_f32_16x16x32_bf16 v[84:87], v[154:157], v[194:197], v[84:87]
	ds_read_b128 v[214:217], v153 offset:3072
	v_mfma_f32_16x16x32_bf16 v[76:79], v[162:165], v[194:197], v[76:79]
	v_mfma_f32_16x16x32_bf16 v[124:127], v[158:161], v[174:177], v[124:127]
	v_mfma_f32_16x16x32_bf16 v[120:123], v[166:169], v[174:177], v[120:123]
	v_mfma_f32_16x16x32_bf16 v[116:119], v[158:161], v[182:185], v[116:119]
	v_mfma_f32_16x16x32_bf16 v[108:111], v[166:169], v[182:185], v[108:111]
	v_mfma_f32_16x16x32_bf16 v[100:103], v[158:161], v[190:193], v[100:103]
	v_mfma_f32_16x16x32_bf16 v[92:95], v[166:169], v[190:193], v[92:95]
	v_mfma_f32_16x16x32_bf16 v[84:87], v[158:161], v[198:201], v[84:87]
	v_mfma_f32_16x16x32_bf16 v[76:79], v[166:169], v[198:201], v[76:79]
	s_barrier
	s_setprio 0
	s_add_i32 s48, 0, 0x1c000
	s_add_i32 s49, s82, s56
	v_add_u32_e32 v153, s48, v148
	s_add_u32 s98, s46, s8
	s_addc_u32 s99, s47, s9
	s_mov_b32 m0, s49
	s_nop 0
	global_load_lds_dwordx4 v136, s[98:99]
	s_add_i32 m0, s49, 0x2000
	s_nop 0
	global_load_lds_dwordx4 v140, s[98:99]
	s_waitcnt lgkmcnt(0)
	s_setprio 1
	s_barrier
	v_mfma_f32_16x16x32_bf16 v[112:115], v[202:205], v[170:173], v[112:115]
	v_mfma_f32_16x16x32_bf16 v[104:107], v[210:213], v[170:173], v[104:107]
	v_mfma_f32_16x16x32_bf16 v[96:99], v[202:205], v[178:181], v[96:99]
	v_mfma_f32_16x16x32_bf16 v[88:91], v[210:213], v[178:181], v[88:91]
	v_mfma_f32_16x16x32_bf16 v[80:83], v[202:205], v[186:189], v[80:83]
	v_mfma_f32_16x16x32_bf16 v[72:75], v[210:213], v[186:189], v[72:75]
	v_mfma_f32_16x16x32_bf16 v[68:71], v[202:205], v[194:197], v[68:71]
	v_mfma_f32_16x16x32_bf16 v[64:67], v[210:213], v[194:197], v[64:67]
	v_mfma_f32_16x16x32_bf16 v[112:115], v[206:209], v[174:177], v[112:115]
	ds_read_b128 v[170:173], v151 offset:49152
	v_mfma_f32_16x16x32_bf16 v[104:107], v[214:217], v[174:177], v[104:107]
	v_mfma_f32_16x16x32_bf16 v[96:99], v[206:209], v[182:185], v[96:99]
	ds_read_b128 v[178:181], v151 offset:51200
	v_mfma_f32_16x16x32_bf16 v[88:91], v[214:217], v[182:185], v[88:91]
	v_mfma_f32_16x16x32_bf16 v[80:83], v[206:209], v[190:193], v[80:83]
	ds_read_b128 v[186:189], v151 offset:53248
	v_mfma_f32_16x16x32_bf16 v[72:75], v[214:217], v[190:193], v[72:75]
	v_mfma_f32_16x16x32_bf16 v[68:71], v[206:209], v[198:201], v[68:71]
	ds_read_b128 v[194:197], v151 offset:55296
	v_mfma_f32_16x16x32_bf16 v[64:67], v[214:217], v[198:201], v[64:67]
	ds_read_b128 v[174:177], v151 offset:50176
	ds_read_b128 v[182:185], v151 offset:52224
	ds_read_b128 v[190:193], v151 offset:54272
	ds_read_b128 v[198:201], v151 offset:56320
	s_barrier
	s_setprio 0
	s_mov_b32 m0, s62
	s_add_u32 s100, s100, s8
	s_addc_u32 s101, s101, s9
	global_load_lds_dwordx4 v134, s[100:101]
	s_mov_b32 m0, s63
	s_nop 0
	global_load_lds_dwordx4 v138, s[100:101]
	s_waitcnt vmcnt(8)
	s_waitcnt lgkmcnt(0)
	s_setprio 1
	s_barrier
	v_mfma_f32_16x16x32_bf16 v[60:63], v[154:157], v[170:173], v[60:63]
	v_mfma_f32_16x16x32_bf16 v[56:59], v[162:165], v[170:173], v[56:59]
	v_mfma_f32_16x16x32_bf16 v[52:55], v[154:157], v[178:181], v[52:55]
	v_mfma_f32_16x16x32_bf16 v[44:47], v[162:165], v[178:181], v[44:47]
	v_mfma_f32_16x16x32_bf16 v[36:39], v[154:157], v[186:189], v[36:39]
	v_mfma_f32_16x16x32_bf16 v[28:31], v[162:165], v[186:189], v[28:31]
	v_mfma_f32_16x16x32_bf16 v[20:23], v[154:157], v[194:197], v[20:23]
	v_mfma_f32_16x16x32_bf16 v[12:15], v[162:165], v[194:197], v[12:15]
	v_mfma_f32_16x16x32_bf16 v[60:63], v[158:161], v[174:177], v[60:63]
	v_mfma_f32_16x16x32_bf16 v[56:59], v[166:169], v[174:177], v[56:59]
	v_mfma_f32_16x16x32_bf16 v[52:55], v[158:161], v[182:185], v[52:55]
	v_mfma_f32_16x16x32_bf16 v[44:47], v[166:169], v[182:185], v[44:47]
	v_mfma_f32_16x16x32_bf16 v[36:39], v[158:161], v[190:193], v[36:39]
	v_mfma_f32_16x16x32_bf16 v[28:31], v[166:169], v[190:193], v[28:31]
	v_mfma_f32_16x16x32_bf16 v[20:23], v[158:161], v[198:201], v[20:23]
	v_mfma_f32_16x16x32_bf16 v[12:15], v[166:169], v[198:201], v[12:15]
	s_barrier
	s_setprio 0
	s_add_u32 s46, s46, 0x100080
	s_addc_u32 s47, s47, 0
	s_add_i32 s48, s48, s56
	s_mov_b32 m0, s48
	s_nop 0
	global_load_lds_dwordx4 v136, s[46:47]
	s_add_i32 m0, s48, 0x2000
	s_nop 0
	global_load_lds_dwordx4 v140, s[46:47]
	s_waitcnt vmcnt(6)
	s_setprio 1
	s_barrier
; __device__ __forceinline__ unsigned cvt_pk_bf16(float lo, float hi) { unsigned r; asm volatile("v_cvt_pk_bf16_f32 %0, %1, %2" : "=v"(r) : "v"(lo), "v"(hi)); return r; }
; #define PG8_STAGE(bufoff, gbase, voff) do { _Pragma("unroll") for (int _i = 0; _i < 2; ++_i) \
;         __builtin_amdgcn_global_load_lds((const unsigned*)((const char*)(gbase) + (voff)[_i]), (LAS unsigned*)(lds + (bufoff) + ldsw + _i * 8192), 16, 0, 0); } while (0)
; #define PG8_MMA(ai, bj, At, Bt) do { __builtin_amdgcn_s_setprio(1); _Pragma("unroll") for (int m = 0; m < 4; ++m) _Pragma("unroll") for (int n = 0; n < 2; ++n) _Pragma("unroll") for (int k = 0; k < 2; ++k) \
;         acc[ai][bj][m][n] = __builtin_amdgcn_mfma_f32_16x16x32_bf16(Bt[n][k], At[m][k], acc[ai][bj][m][n], 0, 0, 0); __builtin_amdgcn_s_setprio(0); } while (0)
; #define PG8_WAIT_V(n) asm volatile("s_waitcnt vmcnt(" #n ")" ::: "memory")
; #define PG8_WAIT_L(n) asm volatile("s_waitcnt lgkmcnt(" #n ")" ::: "memory")
; #define PG8_BAR __builtin_amdgcn_s_barrier()
; #define PG8_SCHED __builtin_amdgcn_sched_barrier(0)
;     __device__ __forceinline__ void operator()(const f32x4 (&acc)[2][2][4][2], const Unit& u, int wr, int wc, int fr, int fq) const {
;         const int row0 = u.orow + wr * 64 + fr, col0 = u.ocol + wc * 32 + 8 * fq;
; #pragma unroll
;         for (int ai = 0; ai < 2; ++ai)
; #pragma unroll
;             for (int m = 0; m < 4; ++m) { bf16_t* rowp = O + (size_t)(row0 + ai * HALF + m * 16) * ldc + col0;
; #pragma unroll
;                 for (int bj = 0; bj < 2; ++bj) { const f32x4 v0 = acc[ai][bj][m][0], v1 = acc[ai][bj][m][1];
;                     u32x4 w; w.x = cvt_pk_bf16(v0[0], v0[1]); w.y = cvt_pk_bf16(v0[2], v0[3]); w.z = cvt_pk_bf16(v1[0], v1[1]); w.w = cvt_pk_bf16(v1[2], v1[3]);
;                     if (nt) __builtin_nontemporal_store(w, (u32x4*)(rowp + bj * HALF)); else *(u32x4*)(rowp + bj * HALF) = w; } }
;     }
; template <class Epi, class Job>
; __device__ __forceinline__ void gemm_phase(LAS unsigned char* lds, const Job& S, const Epi& E) {
;     ...
;             PG8_BAR; PG8_WAIT_L(0); PG8_MMA(1, 0, At, B0); PG8_BAR; PG8_SCHED;
;             PG8_STAGE(PG8_SB(1, 1), b3 + hstepB, voffB);
;             PG8_WAIT_V(6); PG8_BAR; PG8_MMA(1, 1, At, B1); PG8_BAR;
;         }
;         E(acc, cur, wr, wc, fr, fq);
;         if (!has_next) break;
	v_mfma_f32_16x16x32_bf16 v[48:51], v[202:205], v[170:173], v[48:51]
	ds_read_b128 v[154:157], v150
	v_mfma_f32_16x16x32_bf16 v[40:43], v[210:213], v[170:173], v[40:43]
	v_mfma_f32_16x16x32_bf16 v[32:35], v[202:205], v[178:181], v[32:35]
	ds_read_b128 v[158:161], v150 offset:1024
	v_mfma_f32_16x16x32_bf16 v[24:27], v[210:213], v[178:181], v[24:27]
	v_mfma_f32_16x16x32_bf16 v[16:19], v[202:205], v[186:189], v[16:19]
	ds_read_b128 v[162:165], v150 offset:2048
	v_mfma_f32_16x16x32_bf16 v[8:11], v[210:213], v[186:189], v[8:11]
	v_mfma_f32_16x16x32_bf16 v[4:7], v[202:205], v[194:197], v[4:7]
	ds_read_b128 v[166:169], v150 offset:3072
	v_mfma_f32_16x16x32_bf16 v[0:3], v[210:213], v[194:197], v[0:3]
	v_mfma_f32_16x16x32_bf16 v[48:51], v[206:209], v[174:177], v[48:51]
	ds_read_b128 v[170:173], v151
	v_mfma_f32_16x16x32_bf16 v[40:43], v[214:217], v[174:177], v[40:43]
	v_mfma_f32_16x16x32_bf16 v[32:35], v[206:209], v[182:185], v[32:35]
	ds_read_b128 v[178:181], v151 offset:2048
	v_mfma_f32_16x16x32_bf16 v[24:27], v[214:217], v[182:185], v[24:27]
	v_mfma_f32_16x16x32_bf16 v[16:19], v[206:209], v[190:193], v[16:19]
	ds_read_b128 v[186:189], v151 offset:4096
	v_mfma_f32_16x16x32_bf16 v[8:11], v[214:217], v[190:193], v[8:11]
	v_mfma_f32_16x16x32_bf16 v[4:7], v[206:209], v[198:201], v[4:7]
	ds_read_b128 v[194:197], v151 offset:6144
	v_mfma_f32_16x16x32_bf16 v[0:3], v[214:217], v[198:201], v[0:3]
	ds_read_b128 v[174:177], v151 offset:1024
	ds_read_b128 v[182:185], v151 offset:3072
	ds_read_b128 v[190:193], v151 offset:5120
	ds_read_b128 v[198:201], v151 offset:7168
	s_barrier
	s_setprio 0
	s_add_i32 s81, s81, 2
	s_add_u32 s36, s36, 0x100
	s_addc_u32 s37, s37, 0
	s_add_u32 s79, s79, 0x100
	s_addc_u32 s80, s80, 0
	s_cmp_gt_u32 s81, 61
	s_cbranch_scc0 .LBB0_457
	s_waitcnt lgkmcnt(0)
	v_add_u32_e32 v146, s78, v131
	v_ashrrev_i32_e32 v147, 31, v146
	v_add_u32_e32 v154, s77, v149
	v_lshlrev_b64 v[146:147], 13, v[146:147]
	v_ashrrev_i32_e32 v155, 31, v154
	v_lshl_add_u64 v[146:147], s[18:19], 0, v[146:147]
	v_lshl_add_u64 v[146:147], v[154:155], 1, v[146:147]
	v_cvt_pk_bf16_f32 v124, v124, v125
	v_cvt_pk_bf16_f32 v125, v126, v127
	v_cvt_pk_bf16_f32 v126, v120, v121
	v_cvt_pk_bf16_f32 v127, v122, v123
	global_store_dwordx4 v[146:147], v[124:127], off
	v_cvt_pk_bf16_f32 v112, v112, v113
	v_cvt_pk_bf16_f32 v113, v114, v115
	v_cvt_pk_bf16_f32 v114, v104, v105
	v_cvt_pk_bf16_f32 v115, v106, v107
	global_store_dwordx4 v[146:147], v[112:115], off offset:256
	v_cvt_pk_bf16_f32 v104, v116, v117
	v_cvt_pk_bf16_f32 v105, v118, v119
	v_cvt_pk_bf16_f32 v106, v108, v109
	v_add_co_u32_e32 v108, vcc, s68, v146
	s_nop 0
	v_lshl_add_u64 v[112:113], v[146:147], 0, s[10:11]
	v_addc_co_u32_e32 v109, vcc, 0, v147, vcc
	v_cvt_pk_bf16_f32 v107, v110, v111
	global_store_dwordx4 v[108:109], v[104:107], off
	v_cvt_pk_bf16_f32 v96, v96, v97
	v_cvt_pk_bf16_f32 v97, v98, v99
	v_cvt_pk_bf16_f32 v98, v88, v89
	v_cvt_pk_bf16_f32 v99, v90, v91
	global_store_dwordx4 v[112:113], v[96:99], off offset:256
	v_cvt_pk_bf16_f32 v88, v100, v101
	v_cvt_pk_bf16_f32 v89, v102, v103
	v_cvt_pk_bf16_f32 v90, v92, v93
	v_add_co_u32_e32 v92, vcc, s69, v146
	s_nop 0
	v_lshl_add_u64 v[96:97], v[146:147], 0, s[12:13]
	v_addc_co_u32_e32 v93, vcc, 0, v147, vcc
	v_cvt_pk_bf16_f32 v91, v94, v95
	global_store_dwordx4 v[92:93], v[88:91], off
	v_cvt_pk_bf16_f32 v80, v80, v81
	v_cvt_pk_bf16_f32 v81, v82, v83
	v_cvt_pk_bf16_f32 v82, v72, v73
	v_cvt_pk_bf16_f32 v83, v74, v75
	global_store_dwordx4 v[96:97], v[80:83], off offset:256
	v_cvt_pk_bf16_f32 v72, v84, v85
	v_cvt_pk_bf16_f32 v73, v86, v87
	v_cvt_pk_bf16_f32 v74, v76, v77
	v_add_co_u32_e32 v76, vcc, s70, v146
	s_nop 0
	v_lshl_add_u64 v[80:81], v[146:147], 0, s[20:21]
	v_addc_co_u32_e32 v77, vcc, 0, v147, vcc
	v_cvt_pk_bf16_f32 v75, v78, v79
	global_store_dwordx4 v[76:77], v[72:75], off
	v_cvt_pk_bf16_f32 v68, v68, v69
	v_cvt_pk_bf16_f32 v69, v70, v71
	v_cvt_pk_bf16_f32 v70, v64, v65
	v_cvt_pk_bf16_f32 v71, v66, v67
	global_store_dwordx4 v[80:81], v[68:71], off offset:256
	v_cvt_pk_bf16_f32 v60, v60, v61
	v_cvt_pk_bf16_f32 v61, v62, v63
	v_cvt_pk_bf16_f32 v62, v56, v57
	v_add_co_u32_e32 v56, vcc, s71, v146
	v_lshl_add_u64 v[64:65], v[146:147], 0, s[6:7]
	s_nop 0
	v_addc_co_u32_e32 v57, vcc, 0, v147, vcc
	v_cvt_pk_bf16_f32 v63, v58, v59
	global_store_dwordx4 v[56:57], v[60:63], off
	v_cvt_pk_bf16_f32 v48, v48, v49
	v_cvt_pk_bf16_f32 v49, v50, v51
	v_cvt_pk_bf16_f32 v50, v40, v41
	v_cvt_pk_bf16_f32 v51, v42, v43
	global_store_dwordx4 v[64:65], v[48:51], off offset:256
	v_cvt_pk_bf16_f32 v40, v52, v53
	v_cvt_pk_bf16_f32 v41, v54, v55
	v_cvt_pk_bf16_f32 v42, v44, v45
	v_add_co_u32_e32 v44, vcc, s72, v146
	s_nop 0
	v_lshl_add_u64 v[48:49], v[146:147], 0, s[22:23]
	v_addc_co_u32_e32 v45, vcc, 0, v147, vcc
	v_cvt_pk_bf16_f32 v43, v46, v47
	global_store_dwordx4 v[44:45], v[40:43], off
	v_cvt_pk_bf16_f32 v32, v32, v33
	v_cvt_pk_bf16_f32 v33, v34, v35
	v_cvt_pk_bf16_f32 v34, v24, v25
	v_cvt_pk_bf16_f32 v35, v26, v27
	global_store_dwordx4 v[48:49], v[32:35], off offset:256
	v_cvt_pk_bf16_f32 v24, v36, v37
	v_cvt_pk_bf16_f32 v25, v38, v39
	v_cvt_pk_bf16_f32 v26, v28, v29
	v_add_co_u32_e32 v28, vcc, s73, v146
	s_nop 0
	v_lshl_add_u64 v[32:33], v[146:147], 0, s[24:25]
	v_addc_co_u32_e32 v29, vcc, 0, v147, vcc
	v_cvt_pk_bf16_f32 v27, v30, v31
	global_store_dwordx4 v[28:29], v[24:27], off
	v_cvt_pk_bf16_f32 v16, v16, v17
	v_cvt_pk_bf16_f32 v17, v18, v19
	v_cvt_pk_bf16_f32 v18, v8, v9
	v_cvt_pk_bf16_f32 v19, v10, v11
	global_store_dwordx4 v[32:33], v[16:19], off offset:256
	v_cvt_pk_bf16_f32 v8, v20, v21
	v_cvt_pk_bf16_f32 v9, v22, v23
	v_cvt_pk_bf16_f32 v10, v12, v13
	v_add_co_u32_e32 v12, vcc, s74, v146
	s_nop 0
	v_lshl_add_u64 v[16:17], v[146:147], 0, s[26:27]
	v_addc_co_u32_e32 v13, vcc, 0, v147, vcc
	s_and_b64 vcc, exec, s[4:5]
	s_mov_b32 s77, s76
	s_mov_b32 s78, s75
	s_mov_b64 s[46:47], s[30:31]
	s_mov_b64 s[36:37], s[28:29]
	v_cvt_pk_bf16_f32 v11, v14, v15
	global_store_dwordx4 v[12:13], v[8:11], off
	v_cvt_pk_bf16_f32 v4, v4, v5
	v_cvt_pk_bf16_f32 v5, v6, v7
	v_cvt_pk_bf16_f32 v6, v0, v1
	v_cvt_pk_bf16_f32 v7, v2, v3
	global_store_dwordx4 v[16:17], v[4:7], off offset:256
	s_cbranch_vccz .LBB0_450
	s_waitcnt vmcnt(0)
	s_cmpk_gt_u32 s50, 0xff
	s_cbranch_scc1 .LBB0_461
	s_barrier
